# layer-1 small GEMM units in the FFN1-in tail slot + de-serialized norm-gain loads in the tail-slot weight conversions (groups 1-3)
# speedup vs baseline: 1.0037x; 1.0037x over previous
.LBB0_131:
	s_cmpk_gt_i32 s7, 0x57f
	s_cselect_b64 s[2:3], -1, 0
	s_cmpk_lt_i32 s7, 0x580
	s_mov_b64 s[4:5], -1
	s_cbranch_scc0 .LBB0_135
	s_mul_hi_i32 s4, s7, 0x2e8ba2e9
	s_lshr_b32 s5, s4, 31
	s_ashr_i32 s10, s4, 4
	s_add_i32 s10, s10, s5
	s_mul_i32 s5, s10, 0xffffea00
	s_add_i32 s36, s0, s5
	s_lshl_b32 s4, s10, 6
	v_add_u32_e32 v72, s4, v74
	s_ashr_i32 s37, s36, 31
	v_lshl_add_u64 v[56:57], s[36:37], 2, v[66:67]
	s_movk_i32 s11, 0x5800
	v_add_u32_e32 v2, 4, v72
	v_add_u32_e32 v8, 8, v72
	v_add_u32_e32 v10, 12, v72
	v_add_u32_e32 v16, 16, v72
	v_add_u32_e32 v18, 20, v72
	v_add_u32_e32 v24, 24, v72
	v_add_u32_e32 v26, 28, v72
	v_add_u32_e32 v32, 32, v72
	v_add_u32_e32 v34, 36, v72
	v_add_u32_e32 v40, 40, v72
	v_add_u32_e32 v42, 44, v72
	v_add_u32_e32 v48, 48, v72
	v_add_u32_e32 v50, 52, v72
	v_add_u32_e32 v58, 56, v72
	v_add_u32_e32 v60, 60, v72
	v_mad_i64_i32 v[0:1], s[8:9], v72, s11, v[56:57]
	v_mad_i64_i32 v[2:3], s[8:9], v2, s11, v[56:57]
	v_mad_i64_i32 v[8:9], s[8:9], v8, s11, v[56:57]
	v_mad_i64_i32 v[10:11], s[8:9], v10, s11, v[56:57]
	v_mad_i64_i32 v[16:17], s[8:9], v16, s11, v[56:57]
	v_mad_i64_i32 v[18:19], s[8:9], v18, s11, v[56:57]
	v_mad_i64_i32 v[24:25], s[8:9], v24, s11, v[56:57]
	v_mad_i64_i32 v[26:27], s[8:9], v26, s11, v[56:57]
	v_mad_i64_i32 v[32:33], s[8:9], v32, s11, v[56:57]
	v_mad_i64_i32 v[34:35], s[8:9], v34, s11, v[56:57]
	v_mad_i64_i32 v[40:41], s[8:9], v40, s11, v[56:57]
	v_mad_i64_i32 v[42:43], s[8:9], v42, s11, v[56:57]
	v_mad_i64_i32 v[48:49], s[8:9], v48, s11, v[56:57]
	v_mad_i64_i32 v[50:51], s[8:9], v50, s11, v[56:57]
	v_mad_i64_i32 v[58:59], s[8:9], v58, s11, v[56:57]
	v_mad_i64_i32 v[56:57], s[8:9], v60, s11, v[56:57]
	v_readlane_b32 s8, v251, 14
	v_readlane_b32 s9, v251, 15
	s_andn2_b64 vcc, exec, s[8:9]
	s_cbranch_vccnz .Lgk3_nold
	v_readlane_b32 s8, v251, 10
	v_ashrrev_i32_e32 v73, 31, v72
	v_readlane_b32 s9, v251, 11
	s_nop 1
	v_lshl_add_u64 v[72:73], v[72:73], 2, s[8:9]
	global_load_dword v200, v[72:73], off
	global_load_dword v202, v[72:73], off offset:16
	global_load_dword v204, v[72:73], off offset:32
	global_load_dword v206, v[72:73], off offset:48
	global_load_dword v208, v[72:73], off offset:64
	global_load_dword v210, v[72:73], off offset:80
	global_load_dword v212, v[72:73], off offset:96
	global_load_dword v214, v[72:73], off offset:112
	global_load_dword v216, v[72:73], off offset:128
	global_load_dword v218, v[72:73], off offset:144
	global_load_dword v220, v[72:73], off offset:160
	global_load_dword v222, v[72:73], off offset:176
	global_load_dword v224, v[72:73], off offset:192
	global_load_dword v226, v[72:73], off offset:208
	global_load_dword v228, v[72:73], off offset:224
	global_load_dword v230, v[72:73], off offset:240
.Lgk3_nold:
	global_load_dwordx4 v[4:7], v[0:1], off
	s_nop 0
	global_load_dwordx4 v[0:3], v[2:3], off
	s_nop 0
	global_load_dwordx4 v[12:15], v[8:9], off
	s_nop 0
	global_load_dwordx4 v[8:11], v[10:11], off
	s_nop 0
	global_load_dwordx4 v[20:23], v[16:17], off
	s_nop 0
	global_load_dwordx4 v[16:19], v[18:19], off
	s_nop 0
	global_load_dwordx4 v[28:31], v[24:25], off
	s_nop 0
	global_load_dwordx4 v[24:27], v[26:27], off
	s_nop 0
	global_load_dwordx4 v[36:39], v[32:33], off
	s_nop 0
	global_load_dwordx4 v[32:35], v[34:35], off
	s_nop 0
	global_load_dwordx4 v[44:47], v[40:41], off
	s_nop 0
	global_load_dwordx4 v[40:43], v[42:43], off
	s_nop 0
	global_load_dwordx4 v[52:55], v[48:49], off
	s_nop 0
	global_load_dwordx4 v[48:51], v[50:51], off
	s_nop 0
	global_load_dwordx4 v[60:63], v[58:59], off
	s_nop 0
	global_load_dwordx4 v[56:59], v[56:57], off
	v_readlane_b32 s8, v251, 14
	v_readlane_b32 s9, v251, 15
	s_andn2_b64 vcc, exec, s[8:9]
	s_cbranch_vccnz .LBB0_134
	s_waitcnt vmcnt(15)
	v_pk_mul_f32 v[6:7], v[6:7], v[200:201] op_sel_hi:[1,0]
	v_pk_mul_f32 v[4:5], v[4:5], v[200:201] op_sel_hi:[1,0]
	s_waitcnt vmcnt(14)
	v_pk_mul_f32 v[2:3], v[2:3], v[202:203] op_sel_hi:[1,0]
	v_pk_mul_f32 v[0:1], v[0:1], v[202:203] op_sel_hi:[1,0]
	s_waitcnt vmcnt(13)
	v_pk_mul_f32 v[14:15], v[14:15], v[204:205] op_sel_hi:[1,0]
	v_pk_mul_f32 v[12:13], v[12:13], v[204:205] op_sel_hi:[1,0]
	s_waitcnt vmcnt(12)
	v_pk_mul_f32 v[10:11], v[10:11], v[206:207] op_sel_hi:[1,0]
	v_pk_mul_f32 v[8:9], v[8:9], v[206:207] op_sel_hi:[1,0]
	s_waitcnt vmcnt(11)
	v_pk_mul_f32 v[22:23], v[22:23], v[208:209] op_sel_hi:[1,0]
	v_pk_mul_f32 v[20:21], v[20:21], v[208:209] op_sel_hi:[1,0]
	s_waitcnt vmcnt(10)
	v_pk_mul_f32 v[18:19], v[18:19], v[210:211] op_sel_hi:[1,0]
	v_pk_mul_f32 v[16:17], v[16:17], v[210:211] op_sel_hi:[1,0]
	s_waitcnt vmcnt(9)
	v_pk_mul_f32 v[30:31], v[30:31], v[212:213] op_sel_hi:[1,0]
	v_pk_mul_f32 v[28:29], v[28:29], v[212:213] op_sel_hi:[1,0]
	s_waitcnt vmcnt(8)
	v_pk_mul_f32 v[26:27], v[26:27], v[214:215] op_sel_hi:[1,0]
	v_pk_mul_f32 v[24:25], v[24:25], v[214:215] op_sel_hi:[1,0]
	s_waitcnt vmcnt(7)
	v_pk_mul_f32 v[38:39], v[38:39], v[216:217] op_sel_hi:[1,0]
	v_pk_mul_f32 v[36:37], v[36:37], v[216:217] op_sel_hi:[1,0]
	s_waitcnt vmcnt(6)
	v_pk_mul_f32 v[34:35], v[34:35], v[218:219] op_sel_hi:[1,0]
	v_pk_mul_f32 v[32:33], v[32:33], v[218:219] op_sel_hi:[1,0]
	s_waitcnt vmcnt(5)
	v_pk_mul_f32 v[46:47], v[46:47], v[220:221] op_sel_hi:[1,0]
	v_pk_mul_f32 v[44:45], v[44:45], v[220:221] op_sel_hi:[1,0]
	s_waitcnt vmcnt(4)
	v_pk_mul_f32 v[42:43], v[42:43], v[222:223] op_sel_hi:[1,0]
	v_pk_mul_f32 v[40:41], v[40:41], v[222:223] op_sel_hi:[1,0]
	s_waitcnt vmcnt(3)
	v_pk_mul_f32 v[54:55], v[54:55], v[224:225] op_sel_hi:[1,0]
	v_pk_mul_f32 v[52:53], v[52:53], v[224:225] op_sel_hi:[1,0]
	s_waitcnt vmcnt(2)
	v_pk_mul_f32 v[50:51], v[50:51], v[226:227] op_sel_hi:[1,0]
	v_pk_mul_f32 v[48:49], v[48:49], v[226:227] op_sel_hi:[1,0]
	s_waitcnt vmcnt(1)
	v_pk_mul_f32 v[62:63], v[62:63], v[228:229] op_sel_hi:[1,0]
	v_pk_mul_f32 v[60:61], v[60:61], v[228:229] op_sel_hi:[1,0]
	s_waitcnt vmcnt(0)
	v_pk_mul_f32 v[58:59], v[58:59], v[230:231] op_sel_hi:[1,0]
	v_pk_mul_f32 v[56:57], v[56:57], v[230:231] op_sel_hi:[1,0]

.LBB0_182:
	s_cmpk_gt_i32 s6, 0x57f
	s_cselect_b64 s[2:3], -1, 0
	s_cmpk_lt_i32 s6, 0x580
	s_mov_b64 s[4:5], -1
	s_cbranch_scc0 .LBB0_186
	s_mul_hi_i32 s4, s6, 0x2e8ba2e9
	s_lshr_b32 s5, s4, 31
	s_ashr_i32 s4, s4, 4
	s_add_i32 s4, s4, s5
	s_mul_i32 s5, s4, 0x58
	s_sub_i32 s5, s6, s5
	s_lshl_b32 s10, s5, 6
	s_lshl_b32 s4, s4, 6
	v_add_u32_e32 v84, s4, v86
	s_ashr_i32 s11, s10, 31
	v_lshl_add_u64 v[56:57], s[10:11], 2, v[70:71]
	s_movk_i32 s7, 0x5800
	v_add_u32_e32 v2, 4, v84
	v_add_u32_e32 v8, 8, v84
	v_add_u32_e32 v10, 12, v84
	v_add_u32_e32 v16, 16, v84
	v_add_u32_e32 v18, 20, v84
	v_add_u32_e32 v24, 24, v84
	v_add_u32_e32 v26, 28, v84
	v_add_u32_e32 v32, 32, v84
	v_add_u32_e32 v34, 36, v84
	v_add_u32_e32 v40, 40, v84
	v_add_u32_e32 v42, 44, v84
	v_add_u32_e32 v48, 48, v84
	v_add_u32_e32 v50, 52, v84
	v_add_u32_e32 v58, 56, v84
	v_add_u32_e32 v60, 60, v84
	v_mad_i64_i32 v[0:1], s[8:9], v84, s7, v[56:57]
	v_mad_i64_i32 v[2:3], s[8:9], v2, s7, v[56:57]
	v_mad_i64_i32 v[8:9], s[8:9], v8, s7, v[56:57]
	v_mad_i64_i32 v[10:11], s[8:9], v10, s7, v[56:57]
	v_mad_i64_i32 v[16:17], s[8:9], v16, s7, v[56:57]
	v_mad_i64_i32 v[18:19], s[8:9], v18, s7, v[56:57]
	v_mad_i64_i32 v[24:25], s[8:9], v24, s7, v[56:57]
	v_mad_i64_i32 v[26:27], s[8:9], v26, s7, v[56:57]
	v_mad_i64_i32 v[32:33], s[8:9], v32, s7, v[56:57]
	v_mad_i64_i32 v[34:35], s[8:9], v34, s7, v[56:57]
	v_mad_i64_i32 v[40:41], s[8:9], v40, s7, v[56:57]
	v_mad_i64_i32 v[42:43], s[8:9], v42, s7, v[56:57]
	v_mad_i64_i32 v[48:49], s[8:9], v48, s7, v[56:57]
	v_mad_i64_i32 v[50:51], s[8:9], v50, s7, v[56:57]
	v_mad_i64_i32 v[58:59], s[8:9], v58, s7, v[56:57]
	v_mad_i64_i32 v[56:57], s[8:9], v60, s7, v[56:57]
	v_readlane_b32 s8, v251, 14
	v_readlane_b32 s9, v251, 15
	s_andn2_b64 vcc, exec, s[8:9]
	s_cbranch_vccnz .Lgk4_nold
	v_readlane_b32 s36, v250, 16
	v_ashrrev_i32_e32 v85, 31, v84
	v_readlane_b32 s48, v250, 28
	v_readlane_b32 s49, v250, 29
	v_readlane_b32 s37, v250, 17
	v_readlane_b32 s38, v250, 18
	v_lshl_add_u64 v[84:85], v[84:85], 2, s[48:49]
	v_readlane_b32 s39, v250, 19
	v_readlane_b32 s40, v250, 20
	v_readlane_b32 s41, v250, 21
	v_readlane_b32 s42, v250, 22
	v_readlane_b32 s43, v250, 23
	v_readlane_b32 s44, v250, 24
	v_readlane_b32 s45, v250, 25
	v_readlane_b32 s46, v250, 26
	v_readlane_b32 s47, v250, 27
	v_readlane_b32 s50, v250, 30
	v_readlane_b32 s51, v250, 31
	global_load_dword v200, v[84:85], off
	global_load_dword v202, v[84:85], off offset:16
	global_load_dword v204, v[84:85], off offset:32
	global_load_dword v206, v[84:85], off offset:48
	global_load_dword v208, v[84:85], off offset:64
	global_load_dword v210, v[84:85], off offset:80
	global_load_dword v212, v[84:85], off offset:96
	global_load_dword v214, v[84:85], off offset:112
	global_load_dword v216, v[84:85], off offset:128
	global_load_dword v218, v[84:85], off offset:144
	global_load_dword v220, v[84:85], off offset:160
	global_load_dword v222, v[84:85], off offset:176
	global_load_dword v224, v[84:85], off offset:192
	global_load_dword v226, v[84:85], off offset:208
	global_load_dword v228, v[84:85], off offset:224
	global_load_dword v230, v[84:85], off offset:240

.LBB0_1052:
	s_mul_hi_i32 s8, s10, 0x2e8ba2e9
	s_lshr_b32 s9, s8, 31
	s_ashr_i32 s8, s8, 4
	s_add_i32 s8, s8, s9
	s_mul_i32 s9, s8, 0x58
	s_sub_i32 s11, s10, s9
	s_lshl_b32 s36, s11, 6
	s_lshl_b32 s12, s8, 6
	v_add_u32_e32 v92, s12, v124
	s_ashr_i32 s37, s36, 31
	v_lshl_add_u64 v[56:57], s[36:37], 2, v[68:69]
	s_movk_i32 s13, 0x5800
	v_add_u32_e32 v2, 4, v92
	v_add_u32_e32 v8, 8, v92
	v_add_u32_e32 v10, 12, v92
	v_add_u32_e32 v16, 16, v92
	v_add_u32_e32 v18, 20, v92
	v_add_u32_e32 v24, 24, v92
	v_add_u32_e32 v26, 28, v92
	v_add_u32_e32 v32, 32, v92
	v_add_u32_e32 v34, 36, v92
	v_add_u32_e32 v40, 40, v92
	v_add_u32_e32 v42, 44, v92
	v_add_u32_e32 v48, 48, v92
	v_add_u32_e32 v50, 52, v92
	v_add_u32_e32 v58, 56, v92
	v_add_u32_e32 v60, 60, v92
	v_mad_i64_i32 v[0:1], s[8:9], v92, s13, v[56:57]
	v_mad_i64_i32 v[2:3], s[8:9], v2, s13, v[56:57]
	v_mad_i64_i32 v[8:9], s[8:9], v8, s13, v[56:57]
	v_mad_i64_i32 v[10:11], s[8:9], v10, s13, v[56:57]
	v_mad_i64_i32 v[16:17], s[8:9], v16, s13, v[56:57]
	v_mad_i64_i32 v[18:19], s[8:9], v18, s13, v[56:57]
	v_mad_i64_i32 v[24:25], s[8:9], v24, s13, v[56:57]
	v_mad_i64_i32 v[26:27], s[8:9], v26, s13, v[56:57]
	v_mad_i64_i32 v[32:33], s[8:9], v32, s13, v[56:57]
	v_mad_i64_i32 v[34:35], s[8:9], v34, s13, v[56:57]
	v_mad_i64_i32 v[40:41], s[8:9], v40, s13, v[56:57]
	v_mad_i64_i32 v[42:43], s[8:9], v42, s13, v[56:57]
	v_mad_i64_i32 v[48:49], s[8:9], v48, s13, v[56:57]
	v_mad_i64_i32 v[50:51], s[8:9], v50, s13, v[56:57]
	v_mad_i64_i32 v[58:59], s[8:9], v58, s13, v[56:57]
	v_mad_i64_i32 v[56:57], s[8:9], v60, s13, v[56:57]
	v_readlane_b32 s8, v252, 56
	v_readlane_b32 s9, v252, 57
	s_andn2_b64 vcc, exec, s[8:9]
	s_cbranch_vccnz .Lgk5_nold
	v_readlane_b32 s8, v252, 52
	v_ashrrev_i32_e32 v93, 31, v92
	v_readlane_b32 s9, v252, 53
	s_nop 1
	v_lshl_add_u64 v[92:93], v[92:93], 2, s[8:9]
	global_load_dword v200, v[92:93], off
	global_load_dword v202, v[92:93], off offset:16
	global_load_dword v204, v[92:93], off offset:32
	global_load_dword v206, v[92:93], off offset:48
	global_load_dword v208, v[92:93], off offset:64
	global_load_dword v210, v[92:93], off offset:80
	global_load_dword v212, v[92:93], off offset:96
	global_load_dword v214, v[92:93], off offset:112
	global_load_dword v216, v[92:93], off offset:128
	global_load_dword v218, v[92:93], off offset:144
	global_load_dword v220, v[92:93], off offset:160
	global_load_dword v222, v[92:93], off offset:176
	global_load_dword v224, v[92:93], off offset:192
	global_load_dword v226, v[92:93], off offset:208
	global_load_dword v228, v[92:93], off offset:224
	global_load_dword v230, v[92:93], off offset:240
.Lgk5_nold:
	global_load_dwordx4 v[4:7], v[0:1], off
	s_nop 0
	global_load_dwordx4 v[0:3], v[2:3], off
	s_nop 0
	global_load_dwordx4 v[12:15], v[8:9], off
	s_nop 0
	global_load_dwordx4 v[8:11], v[10:11], off
	s_nop 0
	global_load_dwordx4 v[20:23], v[16:17], off
	s_nop 0
	global_load_dwordx4 v[16:19], v[18:19], off
	s_nop 0
	global_load_dwordx4 v[28:31], v[24:25], off
	s_nop 0
	global_load_dwordx4 v[24:27], v[26:27], off
	s_nop 0
	global_load_dwordx4 v[36:39], v[32:33], off
	s_nop 0
	global_load_dwordx4 v[32:35], v[34:35], off
	s_nop 0
	global_load_dwordx4 v[44:47], v[40:41], off
	s_nop 0
	global_load_dwordx4 v[40:43], v[42:43], off
	s_nop 0
	global_load_dwordx4 v[52:55], v[48:49], off
	s_nop 0
	global_load_dwordx4 v[48:51], v[50:51], off
	s_nop 0
	global_load_dwordx4 v[60:63], v[58:59], off
	s_nop 0
	global_load_dwordx4 v[56:59], v[56:57], off
	v_readlane_b32 s8, v252, 56
	v_readlane_b32 s9, v252, 57
	s_andn2_b64 vcc, exec, s[8:9]
	s_cbranch_vccnz .LBB0_1054
	s_waitcnt vmcnt(15)
	v_pk_mul_f32 v[6:7], v[6:7], v[200:201] op_sel_hi:[1,0]
	v_pk_mul_f32 v[4:5], v[4:5], v[200:201] op_sel_hi:[1,0]
	s_waitcnt vmcnt(14)
	v_pk_mul_f32 v[2:3], v[2:3], v[202:203] op_sel_hi:[1,0]
	v_pk_mul_f32 v[0:1], v[0:1], v[202:203] op_sel_hi:[1,0]
	s_waitcnt vmcnt(13)
	v_pk_mul_f32 v[14:15], v[14:15], v[204:205] op_sel_hi:[1,0]
	v_pk_mul_f32 v[12:13], v[12:13], v[204:205] op_sel_hi:[1,0]
	s_waitcnt vmcnt(12)
	v_pk_mul_f32 v[10:11], v[10:11], v[206:207] op_sel_hi:[1,0]
	v_pk_mul_f32 v[8:9], v[8:9], v[206:207] op_sel_hi:[1,0]
	s_waitcnt vmcnt(11)
	v_pk_mul_f32 v[22:23], v[22:23], v[208:209] op_sel_hi:[1,0]
	v_pk_mul_f32 v[20:21], v[20:21], v[208:209] op_sel_hi:[1,0]
	s_waitcnt vmcnt(10)
	v_pk_mul_f32 v[18:19], v[18:19], v[210:211] op_sel_hi:[1,0]
	v_pk_mul_f32 v[16:17], v[16:17], v[210:211] op_sel_hi:[1,0]
	s_waitcnt vmcnt(9)
	v_pk_mul_f32 v[30:31], v[30:31], v[212:213] op_sel_hi:[1,0]
	v_pk_mul_f32 v[28:29], v[28:29], v[212:213] op_sel_hi:[1,0]
	s_waitcnt vmcnt(8)
	v_pk_mul_f32 v[26:27], v[26:27], v[214:215] op_sel_hi:[1,0]
	v_pk_mul_f32 v[24:25], v[24:25], v[214:215] op_sel_hi:[1,0]
	s_waitcnt vmcnt(7)
	v_pk_mul_f32 v[38:39], v[38:39], v[216:217] op_sel_hi:[1,0]
	v_pk_mul_f32 v[36:37], v[36:37], v[216:217] op_sel_hi:[1,0]
	s_waitcnt vmcnt(6)
	v_pk_mul_f32 v[34:35], v[34:35], v[218:219] op_sel_hi:[1,0]
	v_pk_mul_f32 v[32:33], v[32:33], v[218:219] op_sel_hi:[1,0]
	s_waitcnt vmcnt(5)
	v_pk_mul_f32 v[46:47], v[46:47], v[220:221] op_sel_hi:[1,0]
	v_pk_mul_f32 v[44:45], v[44:45], v[220:221] op_sel_hi:[1,0]
	s_waitcnt vmcnt(4)
	v_pk_mul_f32 v[42:43], v[42:43], v[222:223] op_sel_hi:[1,0]
	v_pk_mul_f32 v[40:41], v[40:41], v[222:223] op_sel_hi:[1,0]
	s_waitcnt vmcnt(3)
	v_pk_mul_f32 v[54:55], v[54:55], v[224:225] op_sel_hi:[1,0]
	v_pk_mul_f32 v[52:53], v[52:53], v[224:225] op_sel_hi:[1,0]
	s_waitcnt vmcnt(2)
	v_pk_mul_f32 v[50:51], v[50:51], v[226:227] op_sel_hi:[1,0]
	v_pk_mul_f32 v[48:49], v[48:49], v[226:227] op_sel_hi:[1,0]
	s_waitcnt vmcnt(1)
	v_pk_mul_f32 v[62:63], v[62:63], v[228:229] op_sel_hi:[1,0]
	v_pk_mul_f32 v[60:61], v[60:61], v[228:229] op_sel_hi:[1,0]
	s_waitcnt vmcnt(0)
	v_pk_mul_f32 v[58:59], v[58:59], v[230:231] op_sel_hi:[1,0]
	v_pk_mul_f32 v[56:57], v[56:57], v[230:231] op_sel_hi:[1,0]
